# Fourier stage A publishes with write-through (sc1) output stores and a plain vmcnt(0) drain instead of one whole-L2 release per workgroup
# speedup vs baseline: 1.0159x; 1.0148x over previous
.Lffta_tw:
	v_mov_b32_e32 v88, 0x3b800000
	v_mov_b32_e32 v89, 0x39800000
	v_cndmask_b32_e64 v88, v88, v89, s[42:43]
	v_mul_lo_u32 v89, s0, v125
	v_and_b32_e32 v90, s1, v89
	v_cvt_f32_u32_e32 v90, v90
	v_mul_f32_e32 v90, v88, v90
	v_cos_f32_e32 v91, v90
	v_sin_f32_e32 v90, v90
	s_nop 0
	v_mul_f32_e32 v96, v90, v116
	v_fmac_f32_e32 v96, v91, v84
	v_bfe_u32 v97, v96, 16, 1
	v_mul_f32_e32 v84, v90, v84
	v_add3_u32 v96, v96, v97, s3
	v_fma_f32 v84, v91, v116, -v84
	ds_write_b16_d16_hi v148, v96 offset:34816
	v_bfe_u32 v96, v84, 16, 1
	v_add3_u32 v84, v84, v96, s3
	ds_write_b16_d16_hi v148, v84 offset:34944
	v_mul_f32_e32 v84, v90, v92
	v_fmac_f32_e32 v84, v91, v80
	v_bfe_u32 v96, v84, 16, 1
	v_mul_f32_e32 v80, v90, v80
	v_add3_u32 v84, v84, v96, s3
	v_fma_f32 v80, v91, v92, -v80
	ds_write_b16_d16_hi v148, v84 offset:34848
	v_bfe_u32 v84, v80, 16, 1
	v_add3_u32 v80, v80, v84, s3
	ds_write_b16_d16_hi v148, v80 offset:34976
	v_add_u32_e32 v80, s0, v89
	v_and_b32_e32 v84, s1, v80
	v_cvt_f32_u32_e32 v84, v84
	v_add_u32_e32 v80, s0, v80
	v_mul_f32_e32 v84, v88, v84
	v_cos_f32_e32 v89, v84
	v_sin_f32_e32 v84, v84
	s_nop 0
	v_mul_f32_e32 v90, v84, v117
	v_fmac_f32_e32 v90, v89, v85
	v_bfe_u32 v91, v90, 16, 1
	v_mul_f32_e32 v85, v84, v85
	v_add3_u32 v90, v90, v91, s3
	v_fma_f32 v85, v89, v117, -v85
	ds_write_b16_d16_hi v149, v90 offset:34816
	v_bfe_u32 v90, v85, 16, 1
	v_add3_u32 v85, v85, v90, s3
	ds_write_b16_d16_hi v149, v85 offset:34944
	v_mul_f32_e32 v85, v84, v93
	v_fmac_f32_e32 v85, v89, v81
	v_mul_f32_e32 v81, v84, v81
	v_fma_f32 v81, v89, v93, -v81
	v_bfe_u32 v84, v81, 16, 1
	v_add3_u32 v81, v81, v84, s3
	ds_write_b16_d16_hi v149, v81 offset:34976
	v_and_b32_e32 v81, s1, v80
	v_cvt_f32_u32_e32 v81, v81
	v_bfe_u32 v90, v85, 16, 1
	v_add3_u32 v85, v85, v90, s3
	ds_write_b16_d16_hi v149, v85 offset:34848
	v_mul_f32_e32 v81, v88, v81
	v_cos_f32_e32 v84, v81
	v_sin_f32_e32 v81, v81
	v_add_u32_e32 v80, s0, v80
	v_mul_f32_e32 v85, v81, v118
	v_fmac_f32_e32 v85, v84, v86
	v_bfe_u32 v89, v85, 16, 1
	v_add3_u32 v85, v85, v89, s3
	ds_write_b16_d16_hi v150, v85 offset:34816
	v_mul_f32_e32 v85, v81, v86
	v_fma_f32 v85, v84, v118, -v85
	v_bfe_u32 v86, v85, 16, 1
	v_add3_u32 v85, v85, v86, s3
	ds_write_b16_d16_hi v150, v85 offset:34944
	v_mul_f32_e32 v85, v81, v94
	v_mul_f32_e32 v81, v81, v82
	v_fma_f32 v81, v84, v94, -v81
	v_fmac_f32_e32 v85, v84, v82
	v_bfe_u32 v82, v81, 16, 1
	v_add3_u32 v81, v81, v82, s3
	ds_write_b16_d16_hi v150, v81 offset:34976
	v_and_b32_e32 v81, s1, v80
	v_cvt_f32_u32_e32 v81, v81
	v_bfe_u32 v86, v85, 16, 1
	v_add3_u32 v85, v85, v86, s3
	ds_write_b16_d16_hi v150, v85 offset:34848
	v_mul_f32_e32 v81, v88, v81
	v_cos_f32_e32 v82, v81
	v_sin_f32_e32 v81, v81
	v_add_u32_e32 v80, s16, v80
	v_mul_f32_e32 v84, v81, v119
	v_fmac_f32_e32 v84, v82, v87
	v_bfe_u32 v85, v84, 16, 1
	v_add3_u32 v84, v84, v85, s3
	ds_write_b16_d16_hi v151, v84 offset:34816
	v_mul_f32_e32 v84, v81, v87
	v_fma_f32 v84, v82, v119, -v84
	v_bfe_u32 v85, v84, 16, 1
	v_add3_u32 v84, v84, v85, s3
	ds_write_b16_d16_hi v151, v84 offset:34944
	v_mul_f32_e32 v84, v81, v95
	v_mul_f32_e32 v81, v81, v83
	v_fma_f32 v81, v82, v95, -v81
	v_fmac_f32_e32 v84, v82, v83
	v_bfe_u32 v82, v81, 16, 1
	v_add3_u32 v81, v81, v82, s3
	ds_write_b16_d16_hi v151, v81 offset:34976
	v_and_b32_e32 v81, s1, v80
	v_cvt_f32_u32_e32 v81, v81
	v_bfe_u32 v85, v84, 16, 1
	v_add3_u32 v84, v84, v85, s3
	ds_write_b16_d16_hi v151, v84 offset:34848
	v_mul_f32_e32 v81, v88, v81
	v_cos_f32_e32 v82, v81
	v_sin_f32_e32 v81, v81
	s_nop 0
	v_mul_f32_e32 v83, v81, v76
	v_fmac_f32_e32 v83, v82, v68
	v_mul_f32_e32 v68, v81, v68
	v_fma_f32 v68, v82, v76, -v68
	v_bfe_u32 v76, v68, 16, 1
	v_add3_u32 v68, v68, v76, s3
	ds_write_b16_d16_hi v152, v68 offset:34944
	v_mul_f32_e32 v68, v81, v72
	v_fmac_f32_e32 v68, v82, v64
	v_bfe_u32 v76, v68, 16, 1
	v_mul_f32_e32 v64, v81, v64
	v_add3_u32 v68, v68, v76, s3
	v_fma_f32 v64, v82, v72, -v64
	ds_write_b16_d16_hi v152, v68 offset:34848
	v_bfe_u32 v68, v64, 16, 1
	v_add3_u32 v64, v64, v68, s3
	ds_write_b16_d16_hi v152, v64 offset:34976
	v_add_u32_e32 v64, s0, v80
	v_and_b32_e32 v68, s1, v64
	v_cvt_f32_u32_e32 v68, v68
	v_add_u32_e32 v64, s0, v64
	v_bfe_u32 v84, v83, 16, 1
	v_add3_u32 v83, v83, v84, s3
	v_mul_f32_e32 v68, v88, v68
	v_cos_f32_e32 v72, v68
	v_sin_f32_e32 v68, v68
	ds_write_b16_d16_hi v152, v83 offset:34816
	v_mul_f32_e32 v76, v68, v77
	v_fmac_f32_e32 v76, v72, v69
	v_bfe_u32 v80, v76, 16, 1
	v_mul_f32_e32 v69, v68, v69
	v_add3_u32 v76, v76, v80, s3
	v_fma_f32 v69, v72, v77, -v69
	ds_write_b16_d16_hi v153, v76 offset:34816
	v_bfe_u32 v76, v69, 16, 1
	v_add3_u32 v69, v69, v76, s3
	ds_write_b16_d16_hi v153, v69 offset:34944
	v_mul_f32_e32 v69, v68, v73
	v_fmac_f32_e32 v69, v72, v65
	v_mul_f32_e32 v65, v68, v65
	v_fma_f32 v65, v72, v73, -v65
	v_bfe_u32 v68, v65, 16, 1
	v_add3_u32 v65, v65, v68, s3
	ds_write_b16_d16_hi v153, v65 offset:34976
	v_and_b32_e32 v65, s1, v64
	v_cvt_f32_u32_e32 v65, v65
	v_bfe_u32 v76, v69, 16, 1
	v_add3_u32 v69, v69, v76, s3
	ds_write_b16_d16_hi v153, v69 offset:34848
	v_mul_f32_e32 v65, v88, v65
	v_cos_f32_e32 v68, v65
	v_sin_f32_e32 v65, v65
	v_add_u32_e32 v64, s0, v64
	v_mul_f32_e32 v69, v65, v78
	v_fmac_f32_e32 v69, v68, v70
	v_bfe_u32 v72, v69, 16, 1
	v_add3_u32 v69, v69, v72, s3
	ds_write_b16_d16_hi v154, v69 offset:34816
	v_mul_f32_e32 v69, v65, v70
	v_fma_f32 v69, v68, v78, -v69
	v_bfe_u32 v70, v69, 16, 1
	v_add3_u32 v69, v69, v70, s3
	ds_write_b16_d16_hi v154, v69 offset:34944
	v_mul_f32_e32 v69, v65, v74
	v_mul_f32_e32 v65, v65, v66
	v_fma_f32 v65, v68, v74, -v65
	v_fmac_f32_e32 v69, v68, v66
	v_bfe_u32 v66, v65, 16, 1
	v_add3_u32 v65, v65, v66, s3
	ds_write_b16_d16_hi v154, v65 offset:34976
	v_and_b32_e32 v65, s1, v64
	v_cvt_f32_u32_e32 v65, v65
	v_bfe_u32 v70, v69, 16, 1
	v_add3_u32 v69, v69, v70, s3
	ds_write_b16_d16_hi v154, v69 offset:34848
	v_mul_f32_e32 v65, v88, v65
	v_cos_f32_e32 v66, v65
	v_sin_f32_e32 v65, v65
	v_add_u32_e32 v64, s16, v64
	v_mul_f32_e32 v68, v65, v79
	v_fmac_f32_e32 v68, v66, v71
	v_bfe_u32 v69, v68, 16, 1
	v_add3_u32 v68, v68, v69, s3
	ds_write_b16_d16_hi v155, v68 offset:34816
	v_mul_f32_e32 v68, v65, v71
	v_fma_f32 v68, v66, v79, -v68
	v_bfe_u32 v69, v68, 16, 1
	v_add3_u32 v68, v68, v69, s3
	ds_write_b16_d16_hi v155, v68 offset:34944
	v_mul_f32_e32 v68, v65, v75
	v_mul_f32_e32 v65, v65, v67
	v_fma_f32 v65, v66, v75, -v65
	v_fmac_f32_e32 v68, v66, v67
	v_bfe_u32 v66, v65, 16, 1
	v_add3_u32 v65, v65, v66, s3
	ds_write_b16_d16_hi v155, v65 offset:34976
	v_and_b32_e32 v65, s1, v64
	v_cvt_f32_u32_e32 v65, v65
	v_bfe_u32 v69, v68, 16, 1
	v_add3_u32 v68, v68, v69, s3
	ds_write_b16_d16_hi v155, v68 offset:34848
	v_mul_f32_e32 v65, v88, v65
	v_cos_f32_e32 v66, v65
	v_sin_f32_e32 v65, v65
	s_nop 0
	v_mul_f32_e32 v67, v65, v60
	v_fmac_f32_e32 v67, v66, v52
	v_mul_f32_e32 v52, v65, v52
	v_fma_f32 v52, v66, v60, -v52
	v_bfe_u32 v60, v52, 16, 1
	v_add3_u32 v52, v52, v60, s3
	ds_write_b16_d16_hi v156, v52 offset:34944
	v_mul_f32_e32 v52, v65, v56
	v_fmac_f32_e32 v52, v66, v48
	v_bfe_u32 v60, v52, 16, 1
	v_mul_f32_e32 v48, v65, v48
	v_add3_u32 v52, v52, v60, s3
	v_fma_f32 v48, v66, v56, -v48
	ds_write_b16_d16_hi v156, v52 offset:34848
	v_bfe_u32 v52, v48, 16, 1
	v_add3_u32 v48, v48, v52, s3
	ds_write_b16_d16_hi v156, v48 offset:34976
	v_add_u32_e32 v48, s0, v64
	v_and_b32_e32 v52, s1, v48
	v_cvt_f32_u32_e32 v52, v52
	v_add_u32_e32 v48, s0, v48
	v_bfe_u32 v68, v67, 16, 1
	v_add3_u32 v67, v67, v68, s3
	v_mul_f32_e32 v52, v88, v52
	v_cos_f32_e32 v56, v52
	v_sin_f32_e32 v52, v52
	ds_write_b16_d16_hi v156, v67 offset:34816
	v_mul_f32_e32 v60, v52, v61
	v_fmac_f32_e32 v60, v56, v53
	v_bfe_u32 v64, v60, 16, 1
	v_mul_f32_e32 v53, v52, v53
	v_add3_u32 v60, v60, v64, s3
	v_fma_f32 v53, v56, v61, -v53
	ds_write_b16_d16_hi v157, v60 offset:34816
	v_bfe_u32 v60, v53, 16, 1
	v_add3_u32 v53, v53, v60, s3
	ds_write_b16_d16_hi v157, v53 offset:34944
	v_mul_f32_e32 v53, v52, v57
	v_fmac_f32_e32 v53, v56, v49
	v_mul_f32_e32 v49, v52, v49
	v_fma_f32 v49, v56, v57, -v49
	v_bfe_u32 v52, v49, 16, 1
	v_add3_u32 v49, v49, v52, s3
	ds_write_b16_d16_hi v157, v49 offset:34976
	v_and_b32_e32 v49, s1, v48
	v_cvt_f32_u32_e32 v49, v49
	v_bfe_u32 v60, v53, 16, 1
	v_add3_u32 v53, v53, v60, s3
	ds_write_b16_d16_hi v157, v53 offset:34848
	v_mul_f32_e32 v49, v88, v49
	v_cos_f32_e32 v52, v49
	v_sin_f32_e32 v49, v49
	v_add_u32_e32 v48, s0, v48
	v_mul_f32_e32 v53, v49, v62
	v_fmac_f32_e32 v53, v52, v54
	v_bfe_u32 v56, v53, 16, 1
	v_add3_u32 v53, v53, v56, s3
	ds_write_b16_d16_hi v158, v53 offset:34816
	v_mul_f32_e32 v53, v49, v54
	v_fma_f32 v53, v52, v62, -v53
	v_bfe_u32 v54, v53, 16, 1
	v_add3_u32 v53, v53, v54, s3
	ds_write_b16_d16_hi v158, v53 offset:34944
	v_mul_f32_e32 v53, v49, v58
	v_mul_f32_e32 v49, v49, v50
	v_fma_f32 v49, v52, v58, -v49
	v_fmac_f32_e32 v53, v52, v50
	v_bfe_u32 v50, v49, 16, 1
	v_add3_u32 v49, v49, v50, s3
	ds_write_b16_d16_hi v158, v49 offset:34976
	v_and_b32_e32 v49, s1, v48
	v_cvt_f32_u32_e32 v49, v49
	v_bfe_u32 v54, v53, 16, 1
	v_add3_u32 v53, v53, v54, s3
	ds_write_b16_d16_hi v158, v53 offset:34848
	v_mul_f32_e32 v49, v88, v49
	v_cos_f32_e32 v50, v49
	v_sin_f32_e32 v49, v49
	v_add_u32_e32 v48, s16, v48
	v_mul_f32_e32 v52, v49, v63
	v_fmac_f32_e32 v52, v50, v55
	v_bfe_u32 v53, v52, 16, 1
	v_add3_u32 v52, v52, v53, s3
	ds_write_b16_d16_hi v159, v52 offset:34816
	v_mul_f32_e32 v52, v49, v55
	v_fma_f32 v52, v50, v63, -v52
	v_bfe_u32 v53, v52, 16, 1
	v_add3_u32 v52, v52, v53, s3
	ds_write_b16_d16_hi v159, v52 offset:34944
	v_mul_f32_e32 v52, v49, v59
	v_mul_f32_e32 v49, v49, v51
	v_fma_f32 v49, v50, v59, -v49
	v_fmac_f32_e32 v52, v50, v51
	v_bfe_u32 v50, v49, 16, 1
	v_add3_u32 v49, v49, v50, s3
	ds_write_b16_d16_hi v159, v49 offset:34976
	v_and_b32_e32 v49, s1, v48
	v_cvt_f32_u32_e32 v49, v49
	v_bfe_u32 v53, v52, 16, 1
	v_add3_u32 v52, v52, v53, s3
	ds_write_b16_d16_hi v159, v52 offset:34848
	v_mul_f32_e32 v49, v88, v49
	v_cos_f32_e32 v50, v49
	v_sin_f32_e32 v49, v49
	s_nop 0
	v_mul_f32_e32 v51, v49, v44
	v_fmac_f32_e32 v51, v50, v36
	v_mul_f32_e32 v36, v49, v36
	v_fma_f32 v36, v50, v44, -v36
	v_bfe_u32 v44, v36, 16, 1
	v_add3_u32 v36, v36, v44, s3
	ds_write_b16_d16_hi v160, v36 offset:34944
	v_mul_f32_e32 v36, v49, v40
	v_fmac_f32_e32 v36, v50, v32
	v_bfe_u32 v44, v36, 16, 1
	v_mul_f32_e32 v32, v49, v32
	v_add3_u32 v36, v36, v44, s3
	v_fma_f32 v32, v50, v40, -v32
	ds_write_b16_d16_hi v160, v36 offset:34848
	v_bfe_u32 v36, v32, 16, 1
	v_add3_u32 v32, v32, v36, s3
	ds_write_b16_d16_hi v160, v32 offset:34976
	v_add_u32_e32 v32, s0, v48
	v_and_b32_e32 v36, s1, v32
	v_cvt_f32_u32_e32 v36, v36
	v_add_u32_e32 v32, s0, v32
	v_bfe_u32 v52, v51, 16, 1
	v_add3_u32 v51, v51, v52, s3
	v_mul_f32_e32 v36, v88, v36
	v_cos_f32_e32 v40, v36
	v_sin_f32_e32 v36, v36
	ds_write_b16_d16_hi v160, v51 offset:34816
	v_mul_f32_e32 v44, v36, v45
	v_fmac_f32_e32 v44, v40, v37
	v_bfe_u32 v48, v44, 16, 1
	v_mul_f32_e32 v37, v36, v37
	v_add3_u32 v44, v44, v48, s3
	v_fma_f32 v37, v40, v45, -v37
	ds_write_b16_d16_hi v161, v44 offset:34816
	v_bfe_u32 v44, v37, 16, 1
	v_add3_u32 v37, v37, v44, s3
	ds_write_b16_d16_hi v161, v37 offset:34944
	v_mul_f32_e32 v37, v36, v41
	v_fmac_f32_e32 v37, v40, v33
	v_mul_f32_e32 v33, v36, v33
	v_fma_f32 v33, v40, v41, -v33
	v_bfe_u32 v36, v33, 16, 1
	v_add3_u32 v33, v33, v36, s3
	ds_write_b16_d16_hi v161, v33 offset:34976
	v_and_b32_e32 v33, s1, v32
	v_cvt_f32_u32_e32 v33, v33
	v_bfe_u32 v44, v37, 16, 1
	v_add3_u32 v37, v37, v44, s3
	ds_write_b16_d16_hi v161, v37 offset:34848
	v_mul_f32_e32 v33, v88, v33
	v_cos_f32_e32 v36, v33
	v_sin_f32_e32 v33, v33
	v_add_u32_e32 v32, s0, v32
	v_and_b32_e32 v32, s1, v32
	v_cvt_f32_u32_e32 v32, v32
	v_mul_f32_e32 v37, v33, v46
	v_fmac_f32_e32 v37, v36, v38
	v_bfe_u32 v40, v37, 16, 1
	v_add3_u32 v37, v37, v40, s3
	ds_write_b16_d16_hi v162, v37 offset:34816
	v_mul_f32_e32 v37, v33, v38
	v_fma_f32 v37, v36, v46, -v37
	v_bfe_u32 v38, v37, 16, 1
	v_add3_u32 v37, v37, v38, s3
	ds_write_b16_d16_hi v162, v37 offset:34944
	v_mul_f32_e32 v37, v33, v42
	v_mul_f32_e32 v33, v33, v34
	v_fma_f32 v33, v36, v42, -v33
	v_fmac_f32_e32 v37, v36, v34
	v_bfe_u32 v34, v33, 16, 1
	v_add3_u32 v33, v33, v34, s3
	v_mul_f32_e32 v32, v88, v32
	ds_write_b16_d16_hi v162, v33 offset:34976
	v_cos_f32_e32 v33, v32
	v_sin_f32_e32 v32, v32
	v_bfe_u32 v38, v37, 16, 1
	v_add3_u32 v37, v37, v38, s3
	ds_write_b16_d16_hi v162, v37 offset:34848
	v_mul_f32_e32 v34, v32, v47
	v_fmac_f32_e32 v34, v33, v39
	v_bfe_u32 v36, v34, 16, 1
	v_add3_u32 v34, v34, v36, s3
	ds_write_b16_d16_hi v163, v34 offset:34816
	v_mul_f32_e32 v34, v32, v39
	v_fma_f32 v34, v33, v47, -v34
	v_bfe_u32 v36, v34, 16, 1
	v_add3_u32 v34, v34, v36, s3
	ds_write_b16_d16_hi v163, v34 offset:34944
	v_mul_f32_e32 v34, v32, v43
	v_mul_f32_e32 v32, v32, v35
	v_fmac_f32_e32 v34, v33, v35
	v_fma_f32 v32, v33, v43, -v32
	v_bfe_u32 v36, v34, 16, 1
	v_bfe_u32 v33, v32, 16, 1
	v_add3_u32 v34, v34, v36, s3
	v_add3_u32 v32, v32, v33, s3
	ds_write_b16_d16_hi v163, v34 offset:34848
	ds_write_b16_d16_hi v163, v32 offset:34976
	s_waitcnt lgkmcnt(0)
	s_barrier
	ds_read_b128 v[176:179], v164 offset:34816
	ds_read_b128 v[180:183], v165 offset:34816
	ds_read_b128 v[184:187], v166 offset:34816
	ds_read_b128 v[188:191], v167 offset:34816
	ds_read_b128 v[192:195], v168 offset:34816
	ds_read_b128 v[196:199], v169 offset:34816
	ds_read_b128 v[100:103], v170 offset:34816
	ds_read_b128 v[104:107], v171 offset:34816
	s_lshl_b32 s0, s18, 7
	s_and_b32 s36, s0, 0x380
	v_lshl_add_u64 v[36:37], v[120:121], 0, s[36:37]
	v_mul_u32_u24_e32 v38, s17, v128
	v_add3_u32 v38, s15, v127, v38
	v_ashrrev_i32_e32 v39, 31, v38
	v_lshlrev_b64 v[38:39], 11, v[38:39]
	v_lshl_add_u64 v[38:39], v[36:37], 0, v[38:39]
	s_waitcnt lgkmcnt(7)
	global_store_dwordx4 v[38:39], v[176:179], off sc1
	v_mul_u32_u24_e32 v38, s17, v130
	v_add3_u32 v38, s15, v129, v38
	v_ashrrev_i32_e32 v39, 31, v38
	v_lshlrev_b64 v[38:39], 11, v[38:39]
	v_lshl_add_u64 v[38:39], v[36:37], 0, v[38:39]
	s_waitcnt lgkmcnt(6)
	global_store_dwordx4 v[38:39], v[180:183], off sc1
	v_mul_u32_u24_e32 v38, s17, v132
	v_add3_u32 v38, s15, v131, v38
	v_ashrrev_i32_e32 v39, 31, v38
	v_lshlrev_b64 v[38:39], 11, v[38:39]
	v_lshl_add_u64 v[38:39], v[36:37], 0, v[38:39]
	s_waitcnt lgkmcnt(5)
	global_store_dwordx4 v[38:39], v[184:187], off sc1
	v_mul_u32_u24_e32 v38, s17, v134
	v_add3_u32 v38, s15, v133, v38
	v_ashrrev_i32_e32 v39, 31, v38
	v_lshlrev_b64 v[38:39], 11, v[38:39]
	v_lshl_add_u64 v[38:39], v[36:37], 0, v[38:39]
	s_waitcnt lgkmcnt(4)
	global_store_dwordx4 v[38:39], v[188:191], off sc1
	v_mul_u32_u24_e32 v38, s17, v136
	v_add3_u32 v38, s15, v135, v38
	v_ashrrev_i32_e32 v39, 31, v38
	v_lshlrev_b64 v[38:39], 11, v[38:39]
	v_lshl_add_u64 v[38:39], v[36:37], 0, v[38:39]
	s_waitcnt lgkmcnt(3)
	global_store_dwordx4 v[38:39], v[192:195], off sc1
	v_mul_u32_u24_e32 v38, s17, v138
	v_add3_u32 v38, s15, v137, v38
	v_ashrrev_i32_e32 v39, 31, v38
	v_lshlrev_b64 v[38:39], 11, v[38:39]
	v_lshl_add_u64 v[38:39], v[36:37], 0, v[38:39]
	s_waitcnt lgkmcnt(2)
	global_store_dwordx4 v[38:39], v[196:199], off sc1
	v_mul_u32_u24_e32 v38, s17, v140
	v_add3_u32 v38, s15, v139, v38
	v_ashrrev_i32_e32 v39, 31, v38
	v_lshlrev_b64 v[38:39], 11, v[38:39]
	v_lshl_add_u64 v[38:39], v[36:37], 0, v[38:39]
	s_waitcnt lgkmcnt(1)
	global_store_dwordx4 v[38:39], v[100:103], off sc1
	v_mul_u32_u24_e32 v38, s17, v142
	v_add3_u32 v38, s15, v141, v38
	v_ashrrev_i32_e32 v39, 31, v38
	v_lshlrev_b64 v[38:39], 11, v[38:39]
	v_lshl_add_u64 v[38:39], v[36:37], 0, v[38:39]
	s_waitcnt lgkmcnt(0)
	global_store_dwordx4 v[38:39], v[104:107], off sc1
	s_mul_i32 s0, s10, s54
	s_add_i32 s18, s0, s7
	s_cmpk_lt_i32 s11, 0x480
	s_cbranch_scc0 .LBB0_343

.LBB0_343:
	v_readlane_b32 s0, v255, 6
	v_readlane_b32 s1, v255, 7
	s_mulk_i32 s0, 0xc0
	s_ashr_i32 s1, s0, 31
	s_lshl_b64 s[0:1], s[0:1], 2
	v_readlane_b32 s2, v255, 8
	s_add_u32 s0, s2, s0
	v_readlane_b32 s2, v255, 9
	s_addc_u32 s1, s2, s1
	s_waitcnt lgkmcnt(0)
	s_barrier
	s_waitcnt vmcnt(0)
	s_add_u32 s2, s0, 0x88000
	s_addc_u32 s15, s1, 0
	v_cmp_gt_i32_e32 vcc, 64, v122
	s_barrier
	s_and_saveexec_b64 s[0:1], vcc
	s_cbranch_execz .LBB0_353
	s_waitcnt vmcnt(0)
	s_waitcnt vmcnt(0)
	v_readlane_b32 s4, v253, 47
	v_cmp_eq_u32_e32 vcc, 0, v122
	v_readlane_b32 s5, v253, 48
	s_and_b64 s[10:11], s[4:5], vcc
	s_and_b64 exec, exec, s[10:11]
	s_cbranch_execz .LBB0_353
	s_mov_b32 s16, 0
	s_mov_b32 s17, s7
	s_mov_b32 s11, s7
	s_branch .LBB0_347
